# LRU mt-loop: store addresses via SGPR base + 32-bit voffset (27 fewer VALU per tile), on top of carry-hoist
# speedup vs baseline: 1.1192x; 1.0064x over previous
.LBB0_407:
	s_or_b64 exec, exec, s[0:1]
	v_ashrrev_i32_e32 v36, 2, v161
	v_and_b32_e32 v0, -16, v36
	v_and_b32_e32 v35, 15, v161
	v_add_u32_e32 v0, s5, v0
	v_bfe_u32 v42, v161, 4, 2
	v_or_b32_e32 v32, v0, v35
	v_ashrrev_i32_e32 v33, 31, v32
	s_cmp_lt_i32 s68, 1
	v_cmp_eq_u32_e32 vcc, 0, v42
	s_waitcnt lgkmcnt(0)
	s_barrier
	s_cbranch_scc1 .LBB0_411
	v_readlane_b32 s40, v250, 7
	v_readlane_b32 s41, v250, 8
	v_readlane_b32 s44, v250, 11
	v_readlane_b32 s45, v250, 12
	v_lshlrev_b64 v[0:1], 2, v[32:33]
	s_mov_b64 s[40:41], s[44:45]
	v_lshl_add_u64 v[2:3], s[40:41], 0, v[0:1]
	global_load_dword v37, v[2:3], off
	s_lshr_b32 s0, s31, 3
	v_add_u32_e32 v8, -16, v159
	v_and_b32_e32 v40, 64, v159
	s_and_b32 s6, s0, 7
	v_cmp_lt_i32_e64 s[0:1], v8, v40
	v_readlane_b32 s42, v250, 9
	v_readlane_b32 s43, v250, 10
	v_cndmask_b32_e64 v8, v8, v159, s[0:1]
	s_mov_b32 s0, 0xbfb8aa3b
	v_lshlrev_b64 v[2:3], 8, v[32:33]
	s_mov_b64 s[38:39], s[42:43]
	v_lshlrev_b32_e32 v124, 4, v42
	v_lshl_add_u64 v[4:5], s[14:15], 0, v[2:3]
	v_lshl_add_u64 v[2:3], s[24:25], 0, v[2:3]
	v_lshl_add_u64 v[6:7], s[70:71], 0, v[0:1]
	v_lshl_add_u64 v[0:1], s[38:39], 0, v[0:1]
	v_lshl_add_u64 v[20:21], v[4:5], 0, v[124:125]
	v_lshl_add_u64 v[28:29], v[2:3], 0, v[124:125]
	global_load_dword v45, v[6:7], off
	global_load_dword v46, v[0:1], off
	v_lshlrev_b32_e32 v47, 2, v8
	global_load_dwordx4 v[0:3], v[20:21], off
	global_load_dwordx4 v[4:7], v[20:21], off offset:64
	global_load_dwordx4 v[8:11], v[28:29], off
	global_load_dwordx4 v[12:15], v[28:29], off offset:64
	v_lshlrev_b32_e32 v36, 1, v36
	s_mulk_i32 s6, 0x810
	v_and_b32_e32 v36, 0xffffffe0, v36
	v_lshlrev_b32_e32 v34, 2, v42
	s_add_i32 s6, s6, s4
	v_mov_b32_e32 v44, 0
	v_mov_b32_e32 v43, 1.0
	s_mov_b32 s5, 0
	v_add3_u32 v34, s6, 3, v34
	v_add_u32_e32 v170, -3, v34
	v_lshl_add_u32 v170, v170, 10, v32
	v_lshlrev_b32_e32 v170, 1, v170
	v_add_u32_e32 v171, 0x1000, v170
	v_readlane_b32 s46, v250, 13
	v_readlane_b32 s47, v250, 14
	v_readlane_b32 s48, v250, 15
	v_readlane_b32 s49, v250, 16
	v_readlane_b32 s50, v250, 17
	v_readlane_b32 s51, v250, 18
	v_readlane_b32 s52, v250, 19
	v_readlane_b32 s53, v250, 20
	v_readlane_b32 s54, v250, 21
	v_readlane_b32 s55, v250, 22
	s_waitcnt vmcnt(6)
	v_mul_f32_e32 v16, 0xbfb8aa3b, v37
	v_fma_f32 v17, v37, s0, -v16
	v_rndne_f32_e32 v18, v16
	v_fmac_f32_e32 v17, 0xb2a5705f, v37
	v_sub_f32_e32 v16, v16, v18
	v_add_f32_e32 v16, v16, v17
	v_cvt_i32_f32_e32 v38, v18
	v_exp_f32_e32 v39, v16
	global_load_dwordx4 v[16:19], v[20:21], off offset:128
	s_nop 0
	global_load_dwordx4 v[20:23], v[20:21], off offset:192
	s_nop 0
	global_load_dwordx4 v[24:27], v[28:29], off offset:128
	s_nop 0
	global_load_dwordx4 v[28:31], v[28:29], off offset:192
	s_mov_b32 s0, 0x42ce8ed0
	v_cmp_nlt_f32_e64 s[0:1], s0, v37
	v_ldexp_f32 v38, v39, v38
	s_nop 0
	v_cndmask_b32_e64 v38, 0, v38, s[0:1]
	s_mov_b32 s0, 0xc2b17218
	v_cmp_ngt_f32_e64 s[0:1], s0, v37
	s_nop 1
	v_cndmask_b32_e64 v37, v158, v38, s[0:1]
	v_add_f32_e32 v41, 1.0, v37
	v_add_f32_e32 v48, -1.0, v41
	v_frexp_mant_f32_e32 v49, v41
	v_cvt_f64_f32_e32 v[38:39], v41
	s_mov_b32 s0, 0x3f2aaaab
	v_sub_f32_e32 v50, v48, v41
	v_frexp_exp_i32_f64_e32 v38, v[38:39]
	v_cmp_gt_f32_e64 s[0:1], s0, v49
	v_sub_f32_e32 v48, v37, v48
	v_add_f32_e32 v39, 1.0, v50
	v_subbrev_co_u32_e64 v38, s[0:1], 0, v38, s[0:1]
	v_add_f32_e32 v39, v48, v39
	v_sub_u32_e32 v48, 0, v38
	v_cvt_f32_i32_e32 v38, v38
	v_ldexp_f32 v41, v41, v48
	v_ldexp_f32 v39, v39, v48
	v_add_f32_e32 v48, -1.0, v41
	v_add_f32_e32 v49, 1.0, v41
	v_add_f32_e32 v50, 1.0, v48
	v_add_f32_e32 v51, -1.0, v49
	v_sub_f32_e32 v50, v41, v50
	v_sub_f32_e32 v41, v41, v51
	v_mul_f32_e32 v51, 0x3f317218, v38
	v_add_f32_e32 v50, v39, v50
	v_add_f32_e32 v39, v39, v41
	s_mov_b32 s0, 0x3f317218
	v_fma_f32 v41, v38, s0, -v51
	v_add_f32_e32 v52, v48, v50
	v_add_f32_e32 v53, v49, v39
	v_fmac_f32_e32 v41, 0xb102e308, v38
	v_sub_f32_e32 v38, v48, v52
	v_sub_f32_e32 v48, v49, v53
	v_rcp_f32_e32 v49, v53
	v_add_f32_e32 v54, v51, v41
	v_add_f32_e32 v39, v39, v48
	v_sub_f32_e32 v48, v54, v51
	v_sub_f32_e32 v41, v41, v48
	v_mul_f32_e32 v48, v52, v49
	v_add_f32_e32 v38, v50, v38
	v_mul_f32_e32 v50, v53, v48
	v_fma_f32 v51, v48, v53, -v50
	v_fmac_f32_e32 v51, v48, v39
	v_add_f32_e32 v55, v50, v51
	v_sub_f32_e32 v56, v52, v55
	v_sub_f32_e32 v50, v55, v50
	v_sub_f32_e32 v52, v52, v56
	v_sub_f32_e32 v50, v50, v51
	v_sub_f32_e32 v51, v52, v55
	v_add_f32_e32 v38, v38, v51
	v_add_f32_e32 v38, v50, v38
	v_add_f32_e32 v50, v56, v38
	v_mul_f32_e32 v51, v49, v50
	v_sub_f32_e32 v52, v56, v50
	v_mul_f32_e32 v55, v53, v51
	v_add_f32_e32 v38, v38, v52
	v_add_f32_e32 v52, v48, v51
	v_fma_f32 v53, v51, v53, -v55
	v_sub_f32_e32 v48, v52, v48
	v_fmac_f32_e32 v53, v51, v39
	v_sub_f32_e32 v39, v51, v48
	v_add_f32_e32 v48, v55, v53
	v_sub_f32_e32 v51, v48, v55
	v_sub_f32_e32 v55, v50, v48
	v_sub_f32_e32 v50, v50, v55
	v_sub_f32_e32 v48, v50, v48
	v_sub_f32_e32 v51, v51, v53
	v_add_f32_e32 v38, v38, v48
	v_add_f32_e32 v38, v51, v38
	v_add_f32_e32 v38, v55, v38
	v_mul_f32_e32 v38, v49, v38
	v_add_f32_e32 v38, v39, v38
	v_add_f32_e32 v39, v52, v38
	v_mul_f32_e32 v48, v39, v39
	v_fmamk_f32 v51, v48, 0x3e9b6dac, v127
	v_sub_f32_e32 v49, v39, v52
	v_ldexp_f32 v50, v39, 1
	v_mul_f32_e32 v39, v39, v48
	v_fmaak_f32 v48, v48, v51, 0x3f2aaada
	v_mul_f32_e32 v39, v39, v48
	v_add_f32_e32 v48, v50, v39
	v_sub_f32_e32 v38, v38, v49
	v_sub_f32_e32 v49, v48, v50
	v_ldexp_f32 v38, v38, 1
	v_sub_f32_e32 v39, v39, v49
	v_add_f32_e32 v38, v38, v39
	v_add_f32_e32 v39, v48, v38
	v_sub_f32_e32 v48, v39, v48
	v_add_f32_e32 v49, v54, v39
	v_sub_f32_e32 v38, v38, v48
	v_sub_f32_e32 v48, v49, v54
	v_sub_f32_e32 v50, v49, v48
	v_sub_f32_e32 v39, v39, v48
	v_add_f32_e32 v48, v41, v38
	v_sub_f32_e32 v50, v54, v50
	v_sub_f32_e32 v51, v48, v41
	v_add_f32_e32 v39, v39, v50
	v_sub_f32_e32 v50, v48, v51
	v_sub_f32_e32 v38, v38, v51
	v_sub_f32_e32 v41, v41, v50
	v_add_f32_e32 v39, v48, v39
	v_add_f32_e32 v38, v38, v41
	v_add_f32_e32 v41, v49, v39
	v_sub_f32_e32 v48, v41, v49
	v_sub_f32_e32 v39, v39, v48
	v_add_f32_e32 v38, v38, v39
	s_mov_b32 s0, 0x7f800000
	v_add_f32_e32 v38, v41, v38
	v_cmp_neq_f32_e64 s[0:1], s0, v37
	v_mad_u32_u24 v51, v35, s30, v124
	s_nop 0
	v_cndmask_b32_e64 v38, v158, v38, s[0:1]
	s_mov_b32 s0, 0x33800000
	v_cmp_lt_f32_e64 s[38:39], |v37|, s0
	s_nop 1
	v_cndmask_b32_e64 v37, v38, v37, s[38:39]
	v_mul_f32_e32 v48, 0xc1000000, v37
	v_subrev_u32_e32 v37, 32, v159
	v_cmp_lt_i32_e64 s[0:1], v37, v40
	v_cmp_lt_u32_e64 s[38:39], 1, v42
	s_nop 0
	v_cndmask_b32_e64 v37, v37, v159, s[0:1]
	v_lshlrev_b32_e32 v49, 2, v37
	v_or_b32_e32 v37, v40, v35
	s_movk_i32 s0, 0x440
	v_lshl_or_b32 v50, v37, 2, v160
	v_mad_u32_u24 v37, v42, s0, v36
	v_lshlrev_b32_e32 v35, 1, v35
	v_lshl_add_u32 v36, v42, 10, v36
	v_or_b32_e32 v52, v37, v35
	v_or_b32_e32 v53, v36, v35
	s_waitcnt vmcnt(0)
.LBB0_409:
	v_add_u32_e32 v35, 0, v51
	ds_read_b128 v[36:39], v35
	ds_read_b128 v[58:61], v35 offset:64
	s_add_i32 s5, s5, 1
	v_add_u32_e32 v51, 0x1100, v51
	s_cmp_lt_i32 s5, s68
	s_waitcnt lgkmcnt(1)
	v_mfma_f32_16x16x32_bf16 v[54:57], v[36:39], v[0:3], 0
	v_mfma_f32_16x16x32_bf16 v[36:39], v[36:39], v[8:11], 0
	s_waitcnt lgkmcnt(0)
	v_mfma_f32_16x16x32_bf16 v[54:57], v[58:61], v[4:7], v[54:57]
	v_mfma_f32_16x16x32_bf16 v[36:39], v[58:61], v[12:15], v[36:39]
	ds_read_b128 v[58:61], v35 offset:128
	s_waitcnt lgkmcnt(0)
	v_mfma_f32_16x16x32_bf16 v[54:57], v[58:61], v[16:19], v[54:57]
	v_mfma_f32_16x16x32_bf16 v[36:39], v[58:61], v[24:27], v[36:39]
	ds_read_b128 v[58:61], v35 offset:192
	s_waitcnt lgkmcnt(0)
	v_mfma_f32_16x16x32_bf16 v[62:65], v[58:61], v[20:23], v[54:57]
	s_nop 3
	v_add_u32_e32 v56, 0, v53
	v_add_u32_e32 v54, 0, v52
	v_add_u32_e32 v40, 0x12100, v56
	ds_read_u16 v35, v54
	ds_read_u16 v40, v40
	v_mfma_f32_16x16x32_bf16 v[36:39], v[58:61], v[28:31], v[36:39]
	v_add_u32_e32 v52, 0x1100, v52
	v_add_u32_e32 v53, 0x1000, v53
	s_waitcnt lgkmcnt(0)
	v_lshlrev_b32_e32 v57, 16, v40
	v_add_f32_e32 v40, v45, v62
	v_mul_f32_e32 v40, 0xbfb8aa3b, v40
	v_exp_f32_e32 v40, v40
	s_nop 0
	v_add_f32_e32 v36, v46, v36
	v_mul_f32_e32 v36, 0xbfb8aa3b, v36
	v_exp_f32_e32 v36, v36
	v_add_f32_e32 v40, 1.0, v40
	v_rcp_f32_e32 v40, v40
	v_add_f32_e32 v37, v46, v37
	v_add_f32_e32 v36, 1.0, v36
	v_rcp_f32_e32 v41, v36
	v_mul_f32_e32 v36, v48, v40
	v_mul_f32_e32 v36, 0x3fb8aa3b, v36
	v_exp_f32_e32 v66, v36
	v_add_u32_e32 v40, 0x12200, v56
	ds_read_u16 v40, v40
	v_mul_f32_e32 v37, 0xbfb8aa3b, v37
	v_fma_f32 v36, -v66, v66, 1.0
	v_sqrt_f32_e32 v59, v36
	ds_read_u16 v36, v54 offset:272
	s_waitcnt lgkmcnt(1)
	v_lshlrev_b32_e32 v55, 16, v40
	v_add_f32_e32 v40, v45, v63
	v_mul_f32_e32 v40, 0xbfb8aa3b, v40
	v_exp_f32_e32 v40, v40
	v_exp_f32_e32 v37, v37
	s_waitcnt lgkmcnt(0)
	v_lshlrev_b32_e32 v36, 16, v36
	v_add_f32_e32 v38, v46, v38
	v_add_f32_e32 v40, 1.0, v40
	v_rcp_f32_e32 v58, v40
	v_add_f32_e32 v37, 1.0, v37
	v_rcp_f32_e32 v40, v37
	v_mul_f32_e32 v38, 0xbfb8aa3b, v38
	v_mul_f32_e32 v37, v48, v58
	v_mul_f32_e32 v37, 0x3fb8aa3b, v37
	v_exp_f32_e32 v63, v37
	v_exp_f32_e32 v38, v38
	v_add_f32_e32 v39, v46, v39
	v_mul_f32_e32 v39, 0xbfb8aa3b, v39
	v_fma_f32 v37, -v63, v63, 1.0
	v_sqrt_f32_e32 v58, v37
	v_lshlrev_b32_e32 v37, 16, v35
	v_pk_mul_f32 v[36:37], v[40:41], v[36:37]
	ds_read_u16 v35, v54 offset:544
	v_pk_mul_f32 v[40:41], v[36:37], v[58:59]
	v_add_f32_e32 v37, v45, v64
	v_mul_f32_e32 v37, 0xbfb8aa3b, v37
	v_exp_f32_e32 v37, v37
	v_add_f32_e32 v38, 1.0, v38
	v_rcp_f32_e32 v38, v38
	s_waitcnt lgkmcnt(0)
	v_lshlrev_b32_e32 v36, 16, v35
	v_add_f32_e32 v37, 1.0, v37
	v_rcp_f32_e32 v37, v37
	v_add_u32_e32 v35, 0x12300, v56
	ds_read_u16 v35, v35
	v_mul_f32_e32 v38, v38, v36
	v_mul_f32_e32 v37, v48, v37
	v_mul_f32_e32 v37, 0x3fb8aa3b, v37
	v_exp_f32_e32 v59, v37
	ds_read_u16 v36, v54 offset:816
	v_exp_f32_e32 v39, v39
	v_mul_f32_e32 v57, 0xbfb8aa3b, v57
	v_fma_f32 v37, -v59, v59, 1.0
	v_sqrt_f32_e32 v58, v37
	v_add_u32_e32 v37, 0x12400, v56
	ds_read_u16 v37, v37
	v_add_f32_e32 v39, 1.0, v39
	v_rcp_f32_e32 v39, v39
	s_waitcnt lgkmcnt(1)
	v_lshlrev_b32_e32 v36, 16, v36
	v_exp_f32_e32 v57, v57
	s_waitcnt lgkmcnt(0)
	v_lshlrev_b32_e32 v54, 16, v37
	v_add_f32_e32 v37, v45, v65
	v_mul_f32_e32 v37, 0xbfb8aa3b, v37
	v_exp_f32_e32 v37, v37
	v_mul_f32_e32 v62, v39, v36
	v_fma_f32 v39, v63, v41, v40
	v_mul_f32_e32 v36, v39, v59
	v_add_f32_e32 v37, 1.0, v37
	v_rcp_f32_e32 v37, v37
	v_mul_f32_e32 v40, v63, v66
	v_add_f32_e32 v57, 1.0, v57
	v_rcp_f32_e32 v57, v57
	v_mul_f32_e32 v37, v48, v37
	v_mul_f32_e32 v37, 0x3fb8aa3b, v37
	v_exp_f32_e32 v61, v37
	v_lshlrev_b32_e32 v35, 16, v35
	v_mul_f32_e32 v35, 0xbfb8aa3b, v35
	v_exp_f32_e32 v35, v35
	v_fma_f32 v37, -v61, v61, 1.0
	v_sqrt_f32_e32 v60, v37
	v_pk_fma_f32 v[36:37], v[38:39], v[58:59], v[36:37] op_sel_hi:[1,1,0]
	v_mul_f32_e32 v38, v59, v40
	v_mov_b32_e32 v63, v36
	v_pk_mul_f32 v[58:59], v[60:61], v[62:63]
	v_mul_f32_e32 v60, v61, v38
	v_add_f32_e32 v37, v58, v59
	ds_bpermute_b32 v56, v47, v60
	ds_bpermute_b32 v58, v47, v37
	v_add_f32_e32 v35, 1.0, v35
	v_rcp_f32_e32 v35, v35
	s_waitcnt lgkmcnt(1)
	v_mul_f32_e32 v56, v60, v56
	s_waitcnt lgkmcnt(0)
	v_fma_f32 v58, v60, v58, v37
	v_cndmask_b32_e32 v56, v56, v60, vcc
	v_cndmask_b32_e32 v58, v58, v37, vcc
	ds_bpermute_b32 v59, v49, v56
	ds_bpermute_b32 v61, v49, v58
	s_waitcnt lgkmcnt(1)
	v_mul_f32_e32 v59, v56, v59
	s_waitcnt lgkmcnt(0)
	v_fma_f32 v61, v56, v61, v58
	v_cndmask_b32_e64 v62, v56, v59, s[38:39]
	v_cndmask_b32_e64 v61, v58, v61, s[38:39]
	v_fmac_f32_e32 v61, v44, v62
	ds_bpermute_b32 v56, v47, v61
	ds_bpermute_b32 v58, v47, v62
	s_waitcnt lgkmcnt(1)
	v_cndmask_b32_e32 v44, v56, v44, vcc
	s_waitcnt lgkmcnt(0)
	v_cndmask_b32_e64 v56, v58, 1.0, vcc
	v_mul_f32_e32 v63, v43, v56
	v_fmac_f32_e32 v39, v40, v44
	v_mul_f32_e32 v58, v40, v63
	v_fmac_f32_e32 v37, v60, v44
	v_mul_f32_e32 v40, v60, v63
	v_fmac_f32_e32 v41, v66, v44
	v_fmac_f32_e32 v36, v38, v44
	ds_bpermute_b32 v44, v50, v61
	v_mul_f32_e32 v41, v57, v41
	v_mul_f32_e32 v59, v66, v63
	v_mul_f32_e32 v56, v38, v63
	ds_bpermute_b32 v38, v50, v62
	v_cvt_pk_bf16_f32 v41, v41, v125
	global_store_short v170, v41, s[62:63]
	v_mul_f32_e32 v41, v57, v59
	v_cvt_pk_bf16_f32 v41, v41, v125
	global_store_short v170, v41, s[90:91]
	v_mul_f32_e32 v41, 0xbfb8aa3b, v55
	v_exp_f32_e32 v41, v41
	s_nop 0
	v_add_f32_e32 v41, 1.0, v41
	v_rcp_f32_e32 v41, v41
	s_nop 0
	v_mul_f32_e32 v39, v41, v39
	v_cvt_pk_bf16_f32 v39, v39, v125
	global_store_short v170, v39, s[62:63] offset:2048
	v_mul_f32_e32 v39, v41, v58
	v_cvt_pk_bf16_f32 v39, v39, v125
	global_store_short v170, v39, s[90:91] offset:2048
	v_mul_f32_e32 v36, v35, v36
	v_cvt_pk_bf16_f32 v36, v36, v125
	global_store_short v171, v36, s[62:63]
	v_mul_f32_e32 v36, 0xbfb8aa3b, v54
	v_exp_f32_e32 v36, v36
	v_mul_f32_e32 v35, v35, v56
	v_cvt_pk_bf16_f32 v35, v35, v125
	v_add_f32_e32 v36, 1.0, v36
	v_rcp_f32_e32 v39, v36
	global_store_short v171, v35, s[90:91]
	s_waitcnt lgkmcnt(0)
	v_mul_f32_e32 v43, v43, v38
	v_mul_f32_e32 v36, v39, v37
	v_cvt_pk_bf16_f32 v41, v36, v125
	v_mul_f32_e32 v35, v39, v40
	v_add_u32_e32 v34, 16, v34
	global_store_short v171, v41, s[62:63] offset:2048
	v_cvt_pk_bf16_f32 v35, v35, v125
	global_store_short v171, v35, s[90:91] offset:2048
	v_add_u32_e32 v170, 0x8000, v170
	v_add_u32_e32 v171, 0x8000, v171
	s_cbranch_scc1 .LBB0_409
	v_cmp_eq_u32_e32 vcc, 0, v42
	s_and_saveexec_b64 s[0:1], vcc
	s_cbranch_execz .LBB0_346
	s_branch .LBB0_412
